# layer-0 adaLN GEMV items at kernel start: 32 weight loads per trip in flight together (counted vmcnt), same fma order
# speedup vs baseline: 1.0177x; 1.0086x over previous
; DI void phase_ada_item(CP p, const Ptrs& w, int l, int item, int ksplit, float* sm) {
;     ...
;   const float* wa = p.in[5] + (size_t)l * 2048 * 6144 + j;
;   float a0 = 0.f, a1 = 0.f, a2 = 0.f;
;   const int kb = kq * (2048 / ksplit) + wid * rows_w;
; #pragma unroll 32
;   for (int k = 0; k < rows_w; ++k) {
;     float wv = wa[(size_t)(kb + k) * 6144];
;     a0 += act[kb + k] * wv; a1 += act[2048 + kb + k] * wv; a2 += act[4096 + kb + k] * wv;
.LBB0_39:
	s_or_b64 exec, exec, s[12:13]
	s_mul_hi_i32 s12, s16, 0x2aaaaaab
	s_lshr_b32 s13, s12, 31
	s_ashr_i32 s12, s12, 4
	s_add_i32 s12, s12, s13
	s_mul_i32 s13, s12, 0x60
	v_and_b32_e32 v19, 63, v8
	s_sub_i32 s13, s16, s13
	v_lshl_or_b32 v10, s13, 6, v19
	v_ashrrev_i32_e32 v9, 6, v8
	v_ashrrev_i32_e32 v11, 31, v10
	s_lshl_b32 s12, s12, 9
	v_lshl_add_u32 v2, v9, 7, s12
	v_lshlrev_b64 v[0:1], 2, v[10:11]
	v_mad_i64_i32 v[0:1], s[12:13], v2, s21, v[0:1]
	s_waitcnt vmcnt(2)
	v_mov_b32_e32 v20, 0
	v_lshlrev_b32_e32 v21, 2, v2
	v_lshl_add_u64 v[12:13], s[4:5], 0, v[0:1]
	s_mov_b64 s[12:13], 0
	v_mov_b32_e32 v16, 0
	v_mov_b32_e32 v17, v20
	s_mov_b32 s15, 0x78000
	s_mov_b32 s17, 0x90000
	s_mov_b32 s38, 0xa8000
	s_waitcnt lgkmcnt(0)
	s_barrier
	v_subrev_u32_e32 v156, s4, v12
.LBB0_40:
	s_add_u32 s100, s4, s12
	s_addc_u32 s101, s5, s13
	ds_read_b128 v[0:3], v21
	ds_read_b128 v[4:7], v21 offset:8192
	ds_read_b128 v[22:25], v21 offset:16384
	global_load_dword v96, v156, s[100:101]
	s_add_u32 s100, s100, 0x6000
	s_addc_u32 s101, s101, 0
	global_load_dword v97, v156, s[100:101]
	s_add_u32 s100, s100, 0x6000
	s_addc_u32 s101, s101, 0
	global_load_dword v98, v156, s[100:101]
	s_add_u32 s100, s100, 0x6000
	s_addc_u32 s101, s101, 0
	global_load_dword v99, v156, s[100:101]
	s_add_u32 s100, s100, 0x6000
	s_addc_u32 s101, s101, 0
	global_load_dword v100, v156, s[100:101]
	s_add_u32 s100, s100, 0x6000
	s_addc_u32 s101, s101, 0
	global_load_dword v101, v156, s[100:101]
	s_add_u32 s100, s100, 0x6000
	s_addc_u32 s101, s101, 0
	global_load_dword v102, v156, s[100:101]
	s_add_u32 s100, s100, 0x6000
	s_addc_u32 s101, s101, 0
	global_load_dword v103, v156, s[100:101]
	s_add_u32 s100, s100, 0x6000
	s_addc_u32 s101, s101, 0
	global_load_dword v104, v156, s[100:101]
	s_add_u32 s100, s100, 0x6000
	s_addc_u32 s101, s101, 0
	global_load_dword v105, v156, s[100:101]
	s_add_u32 s100, s100, 0x6000
	s_addc_u32 s101, s101, 0
	global_load_dword v106, v156, s[100:101]
	s_add_u32 s100, s100, 0x6000
	s_addc_u32 s101, s101, 0
	global_load_dword v107, v156, s[100:101]
	s_add_u32 s100, s100, 0x6000
	s_addc_u32 s101, s101, 0
	global_load_dword v108, v156, s[100:101]
	s_add_u32 s100, s100, 0x6000
	s_addc_u32 s101, s101, 0
	global_load_dword v109, v156, s[100:101]
	s_add_u32 s100, s100, 0x6000
	s_addc_u32 s101, s101, 0
	global_load_dword v110, v156, s[100:101]
	s_add_u32 s100, s100, 0x6000
	s_addc_u32 s101, s101, 0
	global_load_dword v111, v156, s[100:101]
	s_add_u32 s100, s100, 0x6000
	s_addc_u32 s101, s101, 0
	global_load_dword v112, v156, s[100:101]
	s_add_u32 s100, s100, 0x6000
	s_addc_u32 s101, s101, 0
	global_load_dword v113, v156, s[100:101]
	s_add_u32 s100, s100, 0x6000
	s_addc_u32 s101, s101, 0
	global_load_dword v114, v156, s[100:101]
	s_add_u32 s100, s100, 0x6000
	s_addc_u32 s101, s101, 0
	global_load_dword v115, v156, s[100:101]
	s_add_u32 s100, s100, 0x6000
	s_addc_u32 s101, s101, 0
	global_load_dword v116, v156, s[100:101]
	s_add_u32 s100, s100, 0x6000
	s_addc_u32 s101, s101, 0
	global_load_dword v117, v156, s[100:101]
	s_add_u32 s100, s100, 0x6000
	s_addc_u32 s101, s101, 0
	global_load_dword v118, v156, s[100:101]
	s_add_u32 s100, s100, 0x6000
	s_addc_u32 s101, s101, 0
	global_load_dword v119, v156, s[100:101]
	s_add_u32 s100, s100, 0x6000
	s_addc_u32 s101, s101, 0
	global_load_dword v120, v156, s[100:101]
	s_add_u32 s100, s100, 0x6000
	s_addc_u32 s101, s101, 0
	global_load_dword v121, v156, s[100:101]
	s_add_u32 s100, s100, 0x6000
	s_addc_u32 s101, s101, 0
	global_load_dword v122, v156, s[100:101]
	s_add_u32 s100, s100, 0x6000
	s_addc_u32 s101, s101, 0
	global_load_dword v123, v156, s[100:101]
	s_add_u32 s100, s100, 0x6000
	s_addc_u32 s101, s101, 0
	global_load_dword v124, v156, s[100:101]
	s_add_u32 s100, s100, 0x6000
	s_addc_u32 s101, s101, 0
	global_load_dword v125, v156, s[100:101]
	s_add_u32 s100, s100, 0x6000
	s_addc_u32 s101, s101, 0
	global_load_dword v126, v156, s[100:101]
	s_add_u32 s100, s100, 0x6000
	s_addc_u32 s101, s101, 0
	global_load_dword v127, v156, s[100:101]
	s_add_u32 s12, s12, 0xc0000
	s_addc_u32 s13, s13, 0
	ds_read_b128 v[26:29], v21 offset:16
	ds_read_b128 v[30:33], v21 offset:8208
	ds_read_b128 v[34:37], v21 offset:16400
	s_waitcnt lgkmcnt(3)
	s_waitcnt vmcnt(31)
	v_fmac_f32_e32 v16, v96, v0
	v_fmac_f32_e32 v17, v96, v4
	v_fmac_f32_e32 v20, v96, v22
	s_waitcnt vmcnt(30)
	v_fmac_f32_e32 v16, v97, v1
	v_fmac_f32_e32 v17, v97, v5
	v_fmac_f32_e32 v20, v97, v23
	s_waitcnt vmcnt(29)
	v_fmac_f32_e32 v16, v98, v2
	v_fmac_f32_e32 v17, v98, v6
	v_fmac_f32_e32 v20, v98, v24
	s_waitcnt vmcnt(28)
	v_fmac_f32_e32 v16, v99, v3
	v_fmac_f32_e32 v17, v99, v7
	v_fmac_f32_e32 v20, v99, v25
	ds_read_b128 v[0:3], v21 offset:32
	ds_read_b128 v[4:7], v21 offset:8224
	ds_read_b128 v[22:25], v21 offset:16416
	s_waitcnt lgkmcnt(3)
	s_waitcnt vmcnt(27)
; DI void phase_ada_item(CP p, const Ptrs& w, int l, int item, int ksplit, float* sm) {
;     ...
;   for (int k = 0; k < rows_w; ++k) {
;     float wv = wa[(size_t)(kb + k) * 6144];
;     a0 += act[kb + k] * wv; a1 += act[2048 + kb + k] * wv; a2 += act[4096 + kb + k] * wv;
;   }
;   red[(wid * 3 + 0) * 64 + lane] = a0; red[(wid * 3 + 1) * 64 + lane] = a1; red[(wid * 3 + 2) * 64 + lane] = a2;
;   __syncthreads();
;   if (tid < 192) {
;     int v = tid >> 6, ll = tid & 63, jj = cgp * 64 + ll;
;     float s = red[(0 * 3 + v) * 64 + ll] + red[(1 * 3 + v) * 64 + ll] + red[(2 * 3 + v) * 64 + ll] + red[(3 * 3 + v) * 64 + ll];
;     if (ksplit == 1) w.mod[(l * 3 + v) * 6144 + jj] = s + p.in[6][l * 6144 + jj];
;     else atomicAdd(&w.mod[(l * 3 + v) * 6144 + jj], kq == 0 ? s + p.in[6][l * 6144 + jj] : s);
	v_fmac_f32_e32 v16, v100, v26
	v_fmac_f32_e32 v17, v100, v30
	v_fmac_f32_e32 v20, v100, v34
	s_waitcnt vmcnt(26)
	v_fmac_f32_e32 v16, v101, v27
	v_fmac_f32_e32 v17, v101, v31
	v_fmac_f32_e32 v20, v101, v35
	s_waitcnt vmcnt(25)
	v_fmac_f32_e32 v16, v102, v28
	v_fmac_f32_e32 v17, v102, v32
	v_fmac_f32_e32 v20, v102, v36
	s_waitcnt vmcnt(24)
	v_fmac_f32_e32 v16, v103, v29
	v_fmac_f32_e32 v17, v103, v33
	v_fmac_f32_e32 v20, v103, v37
	ds_read_b128 v[26:29], v21 offset:48
	ds_read_b128 v[30:33], v21 offset:8240
	ds_read_b128 v[34:37], v21 offset:16432
	s_waitcnt lgkmcnt(3)
	s_waitcnt vmcnt(23)
	v_fmac_f32_e32 v16, v104, v0
	v_fmac_f32_e32 v17, v104, v4
	v_fmac_f32_e32 v20, v104, v22
	s_waitcnt vmcnt(22)
	v_fmac_f32_e32 v16, v105, v1
	v_fmac_f32_e32 v17, v105, v5
	v_fmac_f32_e32 v20, v105, v23
	s_waitcnt vmcnt(21)
	v_fmac_f32_e32 v16, v106, v2
	v_fmac_f32_e32 v17, v106, v6
	v_fmac_f32_e32 v20, v106, v24
	s_waitcnt vmcnt(20)
	v_fmac_f32_e32 v16, v107, v3
	v_fmac_f32_e32 v17, v107, v7
	v_fmac_f32_e32 v20, v107, v25
	ds_read_b128 v[0:3], v21 offset:64
	ds_read_b128 v[4:7], v21 offset:8256
	ds_read_b128 v[22:25], v21 offset:16448
	s_waitcnt lgkmcnt(3)
	s_waitcnt vmcnt(19)
	v_fmac_f32_e32 v16, v108, v26
	v_fmac_f32_e32 v17, v108, v30
	v_fmac_f32_e32 v20, v108, v34
	s_waitcnt vmcnt(18)
	v_fmac_f32_e32 v16, v109, v27
	v_fmac_f32_e32 v17, v109, v31
	v_fmac_f32_e32 v20, v109, v35
	s_waitcnt vmcnt(17)
	v_fmac_f32_e32 v16, v110, v28
	v_fmac_f32_e32 v17, v110, v32
	v_fmac_f32_e32 v20, v110, v36
	s_waitcnt vmcnt(16)
	v_fmac_f32_e32 v16, v111, v29
	v_fmac_f32_e32 v17, v111, v33
	v_fmac_f32_e32 v20, v111, v37
	ds_read_b128 v[26:29], v21 offset:80
	ds_read_b128 v[30:33], v21 offset:8272
	ds_read_b128 v[34:37], v21 offset:16464
	s_waitcnt lgkmcnt(3)
	s_waitcnt vmcnt(15)
	v_fmac_f32_e32 v16, v112, v0
	v_fmac_f32_e32 v17, v112, v4
	v_fmac_f32_e32 v20, v112, v22
	s_waitcnt vmcnt(14)
	v_fmac_f32_e32 v16, v113, v1
	v_fmac_f32_e32 v17, v113, v5
	v_fmac_f32_e32 v20, v113, v23
	s_waitcnt vmcnt(13)
	v_fmac_f32_e32 v16, v114, v2
	v_fmac_f32_e32 v17, v114, v6
	v_fmac_f32_e32 v20, v114, v24
	s_waitcnt vmcnt(12)
	v_fmac_f32_e32 v16, v115, v3
	v_fmac_f32_e32 v17, v115, v7
	v_fmac_f32_e32 v20, v115, v25
	ds_read_b128 v[0:3], v21 offset:96
	ds_read_b128 v[4:7], v21 offset:8288
	ds_read_b128 v[22:25], v21 offset:16480
	s_waitcnt lgkmcnt(3)
	s_waitcnt vmcnt(11)
	v_fmac_f32_e32 v16, v116, v26
	v_fmac_f32_e32 v17, v116, v30
	v_fmac_f32_e32 v20, v116, v34
	s_waitcnt vmcnt(10)
	v_fmac_f32_e32 v16, v117, v27
	v_fmac_f32_e32 v17, v117, v31
	v_fmac_f32_e32 v20, v117, v35
	s_waitcnt vmcnt(9)
	v_fmac_f32_e32 v16, v118, v28
	v_fmac_f32_e32 v17, v118, v32
	v_fmac_f32_e32 v20, v118, v36
	s_waitcnt vmcnt(8)
	v_fmac_f32_e32 v16, v119, v29
	v_fmac_f32_e32 v17, v119, v33
	v_fmac_f32_e32 v20, v119, v37
	ds_read_b128 v[26:29], v21 offset:112
	ds_read_b128 v[30:33], v21 offset:8304
	ds_read_b128 v[34:37], v21 offset:16496
	s_waitcnt lgkmcnt(3)
	s_waitcnt vmcnt(7)
	v_fmac_f32_e32 v16, v120, v0
	v_fmac_f32_e32 v17, v120, v4
	v_fmac_f32_e32 v20, v120, v22
	s_waitcnt vmcnt(6)
	v_fmac_f32_e32 v16, v121, v1
	v_fmac_f32_e32 v17, v121, v5
	v_fmac_f32_e32 v20, v121, v23
	s_waitcnt vmcnt(5)
	v_fmac_f32_e32 v16, v122, v2
	v_fmac_f32_e32 v17, v122, v6
	v_fmac_f32_e32 v20, v122, v24
	s_waitcnt vmcnt(4)
	v_fmac_f32_e32 v16, v123, v3
	v_fmac_f32_e32 v17, v123, v7
	v_fmac_f32_e32 v20, v123, v25
	s_waitcnt lgkmcnt(0)
	s_waitcnt vmcnt(3)
	v_fmac_f32_e32 v16, v124, v26
	v_fmac_f32_e32 v17, v124, v30
	v_fmac_f32_e32 v20, v124, v34
	s_waitcnt vmcnt(2)
	v_fmac_f32_e32 v16, v125, v27
	v_fmac_f32_e32 v17, v125, v31
	v_fmac_f32_e32 v20, v125, v35
	s_waitcnt vmcnt(1)
	v_fmac_f32_e32 v16, v126, v28
	v_fmac_f32_e32 v17, v126, v32
	v_fmac_f32_e32 v20, v126, v36
	s_waitcnt vmcnt(0)
	v_fmac_f32_e32 v16, v127, v29
	v_fmac_f32_e32 v17, v127, v33
	v_fmac_f32_e32 v20, v127, v37
	v_add_u32_e32 v21, 0x80, v21
	s_cmp_eq_u32 s12, 0x300000
	s_cbranch_scc0 .LBB0_40
	s_movk_i32 s12, 0x300
	v_mul_lo_u32 v0, v9, s12
	s_movk_i32 s12, 0xc0
	v_lshl_or_b32 v0, v19, 2, v0
	v_cmp_gt_i32_e32 vcc, s12, v8
	ds_write2st64_b32 v0, v16, v17 offset0:96 offset1:97
	ds_write_b32 v0, v20 offset:25088
	s_waitcnt lgkmcnt(0)
	s_barrier
	s_and_saveexec_b64 s[12:13], vcc
	s_cbranch_execz .LBB0_35
	s_mov_b32 s14, 0x3fffffc0
	v_and_or_b32 v0, v8, s14, v19
	v_lshlrev_b32_e32 v2, 2, v0
	ds_read2st64_b32 v[0:1], v2 offset0:99 offset1:102
	ds_read_b32 v3, v18 offset:24576
	ds_read_b32 v2, v2 offset:26880
	s_add_i32 s14, s16, 0x5f
	s_cmpk_gt_u32 s14, 0xbe
	s_waitcnt lgkmcnt(1)
	v_add_f32_e32 v0, v3, v0
	v_add_f32_e32 v0, v0, v1
	s_waitcnt lgkmcnt(0)
	v_add_f32_e32 v0, v0, v2
	s_cbranch_scc1 .LBB0_34
	v_lshl_add_u64 v[2:3], v[10:11], 2, s[6:7]
	global_load_dword v1, v[2:3], off
	s_waitcnt vmcnt(0)
	v_add_f32_e32 v0, v0, v1
	s_branch .LBB0_34
